# P1 and P8 GEMM epilogue stores marked nt (streaming) so less dirty data waits for the grid barrier's L2 write-back
# baseline (speedup 1.0000x reference)
; __device__ __forceinline__ unsigned pk2(float lo, float hi) { unsigned r; asm volatile("v_cvt_pk_bf16_f32 %0, %1, %2" : "=v"(r) : "v"(lo), "v"(hi)); return r; }
; __device__ __forceinline__ void store8bf(u16* dst, f32x4 v0, f32x4 v1) { u32x4 w; w.x = pk2(v0[0], v0[1]); w.y = pk2(v0[2], v0[3]); w.z = pk2(v1[0], v1[1]); w.w = pk2(v1[2], v1[3]); *(u32x4*)dst = w; }
.LBB0_66:
	s_and_b32 s4, s19, 0x700
	v_or_b32_e32 v138, s4, v157
	v_lshlrev_b32_e32 v138, 1, v138
	v_cvt_pk_bf16_f32 v126, v126, v127
	v_cvt_pk_bf16_f32 v127, v128, v129
	v_cvt_pk_bf16_f32 v128, v122, v123
	v_cndmask_b32_e64 v122, 0, 1, s[24:25]
	v_lshl_add_u64 v[154:155], v[154:155], 0, v[138:139]
	v_cmp_ne_u32_e64 s[4:5], 1, v122
	s_andn2_b64 vcc, exec, s[24:25]
	s_mov_b64 s[24:25], -1
	v_cvt_pk_bf16_f32 v129, v124, v125
	global_store_dwordx4 v[154:155], v[126:129], off nt
	s_cbranch_vccnz .LBB0_73
	s_mov_b64 s[28:29], -1
	s_mov_b64 s[24:25], 0
	s_cmp_lt_i32 s17, 2
	s_mov_b64 s[26:27], 0
	s_cbranch_scc0 .LBB0_206
	s_and_b64 vcc, exec, s[28:29]
	s_cbranch_vccnz .LBB0_209

; __device__ __forceinline__ unsigned pk2(float lo, float hi) { unsigned r; asm volatile("v_cvt_pk_bf16_f32 %0, %1, %2" : "=v"(r) : "v"(lo), "v"(hi)); return r; }
; __device__ __forceinline__ void store8bf(u16* dst, f32x4 v0, f32x4 v1) { u32x4 w; w.x = pk2(v0[0], v0[1]); w.y = pk2(v0[2], v0[3]); w.z = pk2(v1[0], v1[1]); w.w = pk2(v1[2], v1[3]); *(u32x4*)dst = w; }
.LBB0_75:
	v_cvt_pk_bf16_f32 v118, v118, v119
	v_cvt_pk_bf16_f32 v119, v120, v121
	v_cvt_pk_bf16_f32 v120, v114, v115
	v_cvt_pk_bf16_f32 v121, v116, v117
	v_or_b32_e32 v116, 16, v148
	v_ashrrev_i32_e32 v117, 31, v116
	v_lshl_add_u64 v[122:123], v[122:123], 0, v[138:139]
	v_lshlrev_b64 v[114:115], 12, v[116:117]
	v_lshlrev_b64 v[116:117], 13, v[116:117]
	s_and_b64 vcc, exec, s[4:5]
	s_mov_b64 s[24:25], -1
	global_store_dwordx4 v[122:123], v[118:121], off offset:256 nt
	s_cbranch_vccnz .LBB0_82
	s_mov_b64 s[28:29], -1
	s_mov_b64 s[24:25], 0
	s_cmp_lt_i32 s17, 2
	s_mov_b64 s[26:27], 0
	s_cbranch_scc0 .LBB0_211
	s_and_b64 vcc, exec, s[28:29]
	s_cbranch_vccnz .LBB0_214

; __device__ __forceinline__ unsigned pk2(float lo, float hi) { unsigned r; asm volatile("v_cvt_pk_bf16_f32 %0, %1, %2" : "=v"(r) : "v"(lo), "v"(hi)); return r; }
; __device__ __forceinline__ void store8bf(u16* dst, f32x4 v0, f32x4 v1) { u32x4 w; w.x = pk2(v0[0], v0[1]); w.y = pk2(v0[2], v0[3]); w.z = pk2(v1[0], v1[1]); w.w = pk2(v1[2], v1[3]); *(u32x4*)dst = w; }
.LBB0_84:
	v_lshl_add_u64 v[118:119], v[118:119], 0, v[138:139]
	s_and_b64 vcc, exec, s[4:5]
	s_mov_b64 s[24:25], -1
	v_cvt_pk_bf16_f32 v110, v110, v111
	v_cvt_pk_bf16_f32 v111, v112, v113
	v_cvt_pk_bf16_f32 v112, v106, v107
	v_cvt_pk_bf16_f32 v113, v108, v109
	global_store_dwordx4 v[118:119], v[110:113], off nt
	s_cbranch_vccnz .LBB0_91
	s_mov_b64 s[28:29], -1
	s_mov_b64 s[24:25], 0
	s_cmp_lt_i32 s17, 2
	s_mov_b64 s[26:27], 0
	s_cbranch_scc0 .LBB0_216
	s_and_b64 vcc, exec, s[28:29]
	s_cbranch_vccnz .LBB0_219

; __device__ __forceinline__ unsigned pk2(float lo, float hi) { unsigned r; asm volatile("v_cvt_pk_bf16_f32 %0, %1, %2" : "=v"(r) : "v"(lo), "v"(hi)); return r; }
; __device__ __forceinline__ void store8bf(u16* dst, f32x4 v0, f32x4 v1) { u32x4 w; w.x = pk2(v0[0], v0[1]); w.y = pk2(v0[2], v0[3]); w.z = pk2(v1[0], v1[1]); w.w = pk2(v1[2], v1[3]); *(u32x4*)dst = w; }
.LBB0_93:
	v_cvt_pk_bf16_f32 v102, v102, v103
	v_cvt_pk_bf16_f32 v103, v104, v105
	v_cvt_pk_bf16_f32 v104, v98, v99
	v_cvt_pk_bf16_f32 v105, v100, v101
	v_or_b32_e32 v100, 32, v148
	v_ashrrev_i32_e32 v101, 31, v100
	v_lshl_add_u64 v[106:107], v[106:107], 0, v[138:139]
	v_lshlrev_b64 v[98:99], 12, v[100:101]
	v_lshlrev_b64 v[100:101], 13, v[100:101]
	s_and_b64 vcc, exec, s[4:5]
	s_mov_b64 s[24:25], -1
	global_store_dwordx4 v[106:107], v[102:105], off offset:256 nt
	s_cbranch_vccnz .LBB0_100
	s_mov_b64 s[28:29], -1
	s_mov_b64 s[24:25], 0
	s_cmp_lt_i32 s17, 2
	s_mov_b64 s[26:27], 0
	s_cbranch_scc0 .LBB0_221
	s_and_b64 vcc, exec, s[28:29]
	s_cbranch_vccnz .LBB0_224

; __device__ __forceinline__ unsigned pk2(float lo, float hi) { unsigned r; asm volatile("v_cvt_pk_bf16_f32 %0, %1, %2" : "=v"(r) : "v"(lo), "v"(hi)); return r; }
; __device__ __forceinline__ void store8bf(u16* dst, f32x4 v0, f32x4 v1) { u32x4 w; w.x = pk2(v0[0], v0[1]); w.y = pk2(v0[2], v0[3]); w.z = pk2(v1[0], v1[1]); w.w = pk2(v1[2], v1[3]); *(u32x4*)dst = w; }
.LBB0_102:
	v_lshl_add_u64 v[102:103], v[102:103], 0, v[138:139]
	s_and_b64 vcc, exec, s[4:5]
	s_mov_b64 s[24:25], -1
	v_cvt_pk_bf16_f32 v94, v94, v95
	v_cvt_pk_bf16_f32 v95, v96, v97
	v_cvt_pk_bf16_f32 v96, v90, v91
	v_cvt_pk_bf16_f32 v97, v92, v93
	global_store_dwordx4 v[102:103], v[94:97], off nt
	s_cbranch_vccnz .LBB0_109
	s_mov_b64 s[28:29], -1
	s_mov_b64 s[24:25], 0
	s_cmp_lt_i32 s17, 2
	s_mov_b64 s[26:27], 0
	s_cbranch_scc0 .LBB0_226
	s_and_b64 vcc, exec, s[28:29]
	s_cbranch_vccnz .LBB0_229

; __device__ __forceinline__ unsigned pk2(float lo, float hi) { unsigned r; asm volatile("v_cvt_pk_bf16_f32 %0, %1, %2" : "=v"(r) : "v"(lo), "v"(hi)); return r; }
; __device__ __forceinline__ void store8bf(u16* dst, f32x4 v0, f32x4 v1) { u32x4 w; w.x = pk2(v0[0], v0[1]); w.y = pk2(v0[2], v0[3]); w.z = pk2(v1[0], v1[1]); w.w = pk2(v1[2], v1[3]); *(u32x4*)dst = w; }
.LBB0_111:
	v_cvt_pk_bf16_f32 v86, v86, v87
	v_cvt_pk_bf16_f32 v87, v88, v89
	v_cvt_pk_bf16_f32 v88, v82, v83
	v_cvt_pk_bf16_f32 v89, v84, v85
	v_or_b32_e32 v84, 48, v148
	v_ashrrev_i32_e32 v85, 31, v84
	v_lshl_add_u64 v[90:91], v[90:91], 0, v[138:139]
	v_lshlrev_b64 v[82:83], 12, v[84:85]
	v_lshlrev_b64 v[84:85], 13, v[84:85]
	s_and_b64 vcc, exec, s[4:5]
	s_mov_b64 s[24:25], -1
	global_store_dwordx4 v[90:91], v[86:89], off offset:256 nt
	s_cbranch_vccnz .LBB0_118
	s_mov_b64 s[28:29], -1
	s_mov_b64 s[24:25], 0
	s_cmp_lt_i32 s17, 2
	s_mov_b64 s[26:27], 0
	s_cbranch_scc0 .LBB0_231
	s_and_b64 vcc, exec, s[28:29]
	s_cbranch_vccnz .LBB0_234

; __device__ __forceinline__ unsigned pk2(float lo, float hi) { unsigned r; asm volatile("v_cvt_pk_bf16_f32 %0, %1, %2" : "=v"(r) : "v"(lo), "v"(hi)); return r; }
; __device__ __forceinline__ void store8bf(u16* dst, f32x4 v0, f32x4 v1) { u32x4 w; w.x = pk2(v0[0], v0[1]); w.y = pk2(v0[2], v0[3]); w.z = pk2(v1[0], v1[1]); w.w = pk2(v1[2], v1[3]); *(u32x4*)dst = w; }
.LBB0_120:
	v_lshl_add_u64 v[86:87], v[86:87], 0, v[138:139]
	s_and_b64 vcc, exec, s[4:5]
	s_mov_b64 s[24:25], -1
	v_cvt_pk_bf16_f32 v78, v78, v79
	v_cvt_pk_bf16_f32 v79, v80, v81
	v_cvt_pk_bf16_f32 v80, v74, v75
	v_cvt_pk_bf16_f32 v81, v76, v77
	global_store_dwordx4 v[86:87], v[78:81], off nt
	s_cbranch_vccnz .LBB0_127
	s_mov_b64 s[28:29], -1
	s_mov_b64 s[24:25], 0
	s_cmp_lt_i32 s17, 2
	s_mov_b64 s[26:27], 0
	s_cbranch_scc0 .LBB0_236
	s_and_b64 vcc, exec, s[28:29]
	s_cbranch_vccnz .LBB0_239

; __device__ __forceinline__ unsigned pk2(float lo, float hi) { unsigned r; asm volatile("v_cvt_pk_bf16_f32 %0, %1, %2" : "=v"(r) : "v"(lo), "v"(hi)); return r; }
; __device__ __forceinline__ void store8bf(u16* dst, f32x4 v0, f32x4 v1) { u32x4 w; w.x = pk2(v0[0], v0[1]); w.y = pk2(v0[2], v0[3]); w.z = pk2(v1[0], v1[1]); w.w = pk2(v1[2], v1[3]); *(u32x4*)dst = w; }
.LBB0_129:
	v_cvt_pk_bf16_f32 v70, v70, v71
	v_cvt_pk_bf16_f32 v71, v72, v73
	v_cvt_pk_bf16_f32 v72, v66, v67
	v_cvt_pk_bf16_f32 v73, v68, v69
	v_add_u32_e32 v68, 0x80, v148
	v_ashrrev_i32_e32 v69, 31, v68
	v_lshl_add_u64 v[74:75], v[74:75], 0, v[138:139]
	v_lshlrev_b64 v[66:67], 12, v[68:69]
	v_lshlrev_b64 v[68:69], 13, v[68:69]
	s_and_b64 vcc, exec, s[4:5]
	s_mov_b64 s[24:25], -1
	global_store_dwordx4 v[74:75], v[70:73], off offset:256 nt
	s_cbranch_vccnz .LBB0_136
	s_mov_b64 s[28:29], -1
	s_mov_b64 s[24:25], 0
	s_cmp_lt_i32 s17, 2
	s_mov_b64 s[26:27], 0
	s_cbranch_scc0 .LBB0_241
	s_and_b64 vcc, exec, s[28:29]
	s_cbranch_vccnz .LBB0_244

; __device__ __forceinline__ unsigned pk2(float lo, float hi) { unsigned r; asm volatile("v_cvt_pk_bf16_f32 %0, %1, %2" : "=v"(r) : "v"(lo), "v"(hi)); return r; }
; __device__ __forceinline__ void store8bf(u16* dst, f32x4 v0, f32x4 v1) { u32x4 w; w.x = pk2(v0[0], v0[1]); w.y = pk2(v0[2], v0[3]); w.z = pk2(v1[0], v1[1]); w.w = pk2(v1[2], v1[3]); *(u32x4*)dst = w; }
.LBB0_138:
	v_lshl_add_u64 v[70:71], v[70:71], 0, v[138:139]
	s_and_b64 vcc, exec, s[4:5]
	s_mov_b64 s[24:25], -1
	v_cvt_pk_bf16_f32 v62, v62, v63
	v_cvt_pk_bf16_f32 v63, v64, v65
	v_cvt_pk_bf16_f32 v64, v58, v59
	v_cvt_pk_bf16_f32 v65, v60, v61
	global_store_dwordx4 v[70:71], v[62:65], off nt
	s_cbranch_vccnz .LBB0_145
	s_mov_b64 s[28:29], -1
	s_mov_b64 s[24:25], 0
	s_cmp_lt_i32 s17, 2
	s_mov_b64 s[26:27], 0
	s_cbranch_scc0 .LBB0_246
	s_and_b64 vcc, exec, s[28:29]
	s_cbranch_vccnz .LBB0_249

; __device__ __forceinline__ unsigned pk2(float lo, float hi) { unsigned r; asm volatile("v_cvt_pk_bf16_f32 %0, %1, %2" : "=v"(r) : "v"(lo), "v"(hi)); return r; }
; __device__ __forceinline__ void store8bf(u16* dst, f32x4 v0, f32x4 v1) { u32x4 w; w.x = pk2(v0[0], v0[1]); w.y = pk2(v0[2], v0[3]); w.z = pk2(v1[0], v1[1]); w.w = pk2(v1[2], v1[3]); *(u32x4*)dst = w; }
.LBB0_147:
	v_cvt_pk_bf16_f32 v54, v54, v55
	v_cvt_pk_bf16_f32 v55, v56, v57
	v_cvt_pk_bf16_f32 v56, v50, v51
	v_cvt_pk_bf16_f32 v57, v52, v53
	v_add_u32_e32 v52, 0x90, v148
	v_ashrrev_i32_e32 v53, 31, v52
	v_lshl_add_u64 v[58:59], v[58:59], 0, v[138:139]
	v_lshlrev_b64 v[50:51], 12, v[52:53]
	v_lshlrev_b64 v[52:53], 13, v[52:53]
	s_and_b64 vcc, exec, s[4:5]
	s_mov_b64 s[24:25], -1
	global_store_dwordx4 v[58:59], v[54:57], off offset:256 nt
	s_cbranch_vccnz .LBB0_154
	s_mov_b64 s[28:29], -1
	s_mov_b64 s[24:25], 0
	s_cmp_lt_i32 s17, 2
	s_mov_b64 s[26:27], 0
	s_cbranch_scc0 .LBB0_251
	s_and_b64 vcc, exec, s[28:29]
	s_cbranch_vccnz .LBB0_254

; __device__ __forceinline__ unsigned pk2(float lo, float hi) { unsigned r; asm volatile("v_cvt_pk_bf16_f32 %0, %1, %2" : "=v"(r) : "v"(lo), "v"(hi)); return r; }
; __device__ __forceinline__ void store8bf(u16* dst, f32x4 v0, f32x4 v1) { u32x4 w; w.x = pk2(v0[0], v0[1]); w.y = pk2(v0[2], v0[3]); w.z = pk2(v1[0], v1[1]); w.w = pk2(v1[2], v1[3]); *(u32x4*)dst = w; }
.LBB0_156:
	v_lshl_add_u64 v[54:55], v[54:55], 0, v[138:139]
	s_and_b64 vcc, exec, s[4:5]
	s_mov_b64 s[24:25], -1
	v_cvt_pk_bf16_f32 v46, v46, v47
	v_cvt_pk_bf16_f32 v47, v48, v49
	v_cvt_pk_bf16_f32 v48, v42, v43
	v_cvt_pk_bf16_f32 v49, v44, v45
	global_store_dwordx4 v[54:55], v[46:49], off nt
	s_cbranch_vccnz .LBB0_163
	s_mov_b64 s[28:29], -1
	s_mov_b64 s[24:25], 0
	s_cmp_lt_i32 s17, 2
	s_mov_b64 s[26:27], 0
	s_cbranch_scc0 .LBB0_256
	s_and_b64 vcc, exec, s[28:29]
	s_cbranch_vccnz .LBB0_259

; __device__ __forceinline__ unsigned pk2(float lo, float hi) { unsigned r; asm volatile("v_cvt_pk_bf16_f32 %0, %1, %2" : "=v"(r) : "v"(lo), "v"(hi)); return r; }
; __device__ __forceinline__ void store8bf(u16* dst, f32x4 v0, f32x4 v1) { u32x4 w; w.x = pk2(v0[0], v0[1]); w.y = pk2(v0[2], v0[3]); w.z = pk2(v1[0], v1[1]); w.w = pk2(v1[2], v1[3]); *(u32x4*)dst = w; }
.LBB0_165:
	v_cvt_pk_bf16_f32 v38, v38, v39
	v_cvt_pk_bf16_f32 v39, v40, v41
	v_cvt_pk_bf16_f32 v40, v34, v35
	v_cvt_pk_bf16_f32 v41, v36, v37
	v_add_u32_e32 v36, 0xa0, v148
	v_ashrrev_i32_e32 v37, 31, v36
	v_lshl_add_u64 v[42:43], v[42:43], 0, v[138:139]
	v_lshlrev_b64 v[34:35], 12, v[36:37]
	v_lshlrev_b64 v[36:37], 13, v[36:37]
	s_and_b64 vcc, exec, s[4:5]
	s_mov_b64 s[24:25], -1
	global_store_dwordx4 v[42:43], v[38:41], off offset:256 nt
	s_cbranch_vccnz .LBB0_172
	s_mov_b64 s[28:29], -1
	s_mov_b64 s[24:25], 0
	s_cmp_lt_i32 s17, 2
	s_mov_b64 s[26:27], 0
	s_cbranch_scc0 .LBB0_261
	s_and_b64 vcc, exec, s[28:29]
	s_cbranch_vccnz .LBB0_264

; __device__ __forceinline__ unsigned pk2(float lo, float hi) { unsigned r; asm volatile("v_cvt_pk_bf16_f32 %0, %1, %2" : "=v"(r) : "v"(lo), "v"(hi)); return r; }
; __device__ __forceinline__ void store8bf(u16* dst, f32x4 v0, f32x4 v1) { u32x4 w; w.x = pk2(v0[0], v0[1]); w.y = pk2(v0[2], v0[3]); w.z = pk2(v1[0], v1[1]); w.w = pk2(v1[2], v1[3]); *(u32x4*)dst = w; }
.LBB0_174:
	v_lshl_add_u64 v[38:39], v[38:39], 0, v[138:139]
	s_and_b64 vcc, exec, s[4:5]
	s_mov_b64 s[24:25], -1
	v_cvt_pk_bf16_f32 v30, v30, v31
	v_cvt_pk_bf16_f32 v31, v32, v33
	v_cvt_pk_bf16_f32 v32, v26, v27
	v_cvt_pk_bf16_f32 v33, v28, v29
	global_store_dwordx4 v[38:39], v[30:33], off nt
	s_cbranch_vccnz .LBB0_181
	s_mov_b64 s[28:29], -1
	s_mov_b64 s[24:25], 0
	s_cmp_lt_i32 s17, 2
	s_mov_b64 s[26:27], 0
	s_cbranch_scc0 .LBB0_266
	s_and_b64 vcc, exec, s[28:29]
	s_cbranch_vccnz .LBB0_269

; __device__ __forceinline__ unsigned pk2(float lo, float hi) { unsigned r; asm volatile("v_cvt_pk_bf16_f32 %0, %1, %2" : "=v"(r) : "v"(lo), "v"(hi)); return r; }
; __device__ __forceinline__ void store8bf(u16* dst, f32x4 v0, f32x4 v1) { u32x4 w; w.x = pk2(v0[0], v0[1]); w.y = pk2(v0[2], v0[3]); w.z = pk2(v1[0], v1[1]); w.w = pk2(v1[2], v1[3]); *(u32x4*)dst = w; }
.LBB0_183:
	v_cvt_pk_bf16_f32 v22, v22, v23
	v_cvt_pk_bf16_f32 v23, v24, v25
	v_cvt_pk_bf16_f32 v24, v18, v19
	v_cvt_pk_bf16_f32 v25, v20, v21
	v_add_u32_e32 v20, 0xb0, v148
	v_ashrrev_i32_e32 v21, 31, v20
	v_lshl_add_u64 v[26:27], v[26:27], 0, v[138:139]
	v_lshlrev_b64 v[18:19], 12, v[20:21]
	v_lshlrev_b64 v[20:21], 13, v[20:21]
	s_and_b64 vcc, exec, s[4:5]
	s_mov_b64 s[24:25], -1
	global_store_dwordx4 v[26:27], v[22:25], off offset:256 nt
	s_cbranch_vccnz .LBB0_190
	s_mov_b64 s[28:29], -1
	s_mov_b64 s[24:25], 0
	s_cmp_lt_i32 s17, 2
	s_mov_b64 s[26:27], 0
	s_cbranch_scc0 .LBB0_271
	s_and_b64 vcc, exec, s[28:29]
	s_cbranch_vccnz .LBB0_274

; __device__ __forceinline__ unsigned pk2(float lo, float hi) { unsigned r; asm volatile("v_cvt_pk_bf16_f32 %0, %1, %2" : "=v"(r) : "v"(lo), "v"(hi)); return r; }
; __device__ __forceinline__ void store8bf(u16* dst, f32x4 v0, f32x4 v1) { u32x4 w; w.x = pk2(v0[0], v0[1]); w.y = pk2(v0[2], v0[3]); w.z = pk2(v1[0], v1[1]); w.w = pk2(v1[2], v1[3]); *(u32x4*)dst = w; }
.LBB0_192:
	v_lshl_add_u64 v[22:23], v[22:23], 0, v[138:139]
	s_and_b64 vcc, exec, s[4:5]
	s_mov_b64 s[4:5], -1
	v_cvt_pk_bf16_f32 v14, v14, v15
	v_cvt_pk_bf16_f32 v15, v16, v17
	v_cvt_pk_bf16_f32 v16, v10, v11
	v_cvt_pk_bf16_f32 v17, v12, v13
	global_store_dwordx4 v[22:23], v[14:17], off nt
	s_cbranch_vccnz .LBB0_199
	s_mov_b64 s[26:27], -1
	s_mov_b64 s[4:5], 0
	s_cmp_lt_i32 s17, 2
	s_mov_b64 s[24:25], 0
	s_cbranch_scc0 .LBB0_276
	s_and_b64 vcc, exec, s[26:27]
	s_cbranch_vccnz .LBB0_279

; #define PG8_STAGE(bufoff, gbase, voff) do { _Pragma("unroll") for (int _i = 0; _i < 2; ++_i) \
;         __builtin_amdgcn_global_load_lds((const unsigned*)((const char*)(gbase) + (voff)[_i]), (PG8_LAS unsigned*)(lds + (bufoff) + ldsw + _i * 8192), 16, 0, 0); } while (0)
; #define PG8_LDA(dst, b, h) do { _Pragma("unroll") for (int m = 0; m < 4; ++m) _Pragma("unroll") for (int k = 0; k < 2; ++k) dst[m][k] = *(const PG8_LAS bf16x8*)(lds + PG8_SA(b, h) + aoff + m * 2048 + k * 1024); } while (0)
; #define PG8_LDB(dst, b, h) do { _Pragma("unroll") for (int n = 0; n < 2; ++n) _Pragma("unroll") for (int k = 0; k < 2; ++k) dst[n][k] = *(const PG8_LAS bf16x8*)(lds + PG8_SB(b, h) + boff + n * 2048 + k * 1024); } while (0)
; #define PG8_MMA(ai, bj, At, Bt) do { __builtin_amdgcn_s_setprio(1); _Pragma("unroll") for (int m = 0; m < 4; ++m) _Pragma("unroll") for (int n = 0; n < 2; ++n) _Pragma("unroll") for (int k = 0; k < 2; ++k) \
;         acc[ai][bj][m][n] = __builtin_amdgcn_mfma_f32_16x16x32_bf16(Bt[n][k], At[m][k], acc[ai][bj][m][n], 0, 0, 0); __builtin_amdgcn_s_setprio(0); } while (0)
; #define PG8_WAIT_V(n) asm volatile("s_waitcnt vmcnt(" #n ")" ::: "memory")
; #define PG8_WAIT_L(n) asm volatile("s_waitcnt lgkmcnt(" #n ")" ::: "memory")
; #define PG8_BAR __builtin_amdgcn_s_barrier()
; #define PG8_SCHED __builtin_amdgcn_sched_barrier(0)
; template <class Epi>
; __device__ __forceinline__ void gemm_phase(PG8_LAS unsigned char* lds, const Gemm g, const StaticOrder& S, const Epi& E) {
;     ...
;             PG8_LDB(B0, 0, 0); PG8_SCHED; PG8_LDA(At, 0, 0); PG8_STAGE(PG8_SA(1, 1), a1 + hstep, voffA);
;             PG8_WAIT_L(8); PG8_BAR; PG8_WAIT_L(0); PG8_MMA(0, 0, At, B0); PG8_BAR; PG8_SCHED;
;             PG8_LDB(B1, 0, 1); PG8_STAGE(PG8_SB(0, 0), b2, voffB);
;             PG8_BAR; PG8_WAIT_L(0); PG8_MMA(0, 1, At, B1); PG8_BAR;
;             PG8_LDA(At, 0, 1); PG8_STAGE(PG8_SA(0, 0), a2, voffA);
;             PG8_BAR; PG8_WAIT_L(0); PG8_MMA(1, 0, At, B0); PG8_BAR; PG8_SCHED;
;             PG8_STAGE(PG8_SB(0, 1), b2 + hstep, voffB);
;             PG8_WAIT_V(6); PG8_BAR; PG8_MMA(1, 1, At, B1); PG8_BAR;
.LBB0_722:
	ds_read_b128 v[150:153], v159
	ds_read_b128 v[154:157], v159 offset:1024
	ds_read_b128 v[162:165], v159 offset:2048
	ds_read_b128 v[166:169], v159 offset:3072
	s_add_u32 s22, s20, 0xfff80080
	s_addc_u32 s23, s21, -1
	s_cmp_eq_u32 s50, 28
	s_cselect_b32 s25, s3, s23
	s_cselect_b32 s24, s5, s22
	s_cselect_b32 s23, s13, s49
	s_cselect_b32 s22, s15, s48
	v_lshl_add_u64 v[202:203], s[20:21], 0, v[142:143]
	s_add_i32 m0, s30, 0xc000
	ds_read_b128 v[170:173], v160
	ds_read_b128 v[174:177], v160 offset:1024
	ds_read_b128 v[178:181], v160 offset:2048
	ds_read_b128 v[182:185], v160 offset:3072
	ds_read_b128 v[186:189], v160 offset:4096
	ds_read_b128 v[190:193], v160 offset:5120
	ds_read_b128 v[194:197], v160 offset:6144
	ds_read_b128 v[198:201], v160 offset:7168
	global_load_lds_dwordx4 v[202:203], off
	v_lshl_add_u64 v[202:203], s[20:21], 0, v[144:145]
	s_add_i32 m0, s30, 0xe000
	s_nop 0
	global_load_lds_dwordx4 v[202:203], off
	s_waitcnt lgkmcnt(8)
	s_barrier
	s_waitcnt lgkmcnt(0)
	s_setprio 1
	s_waitcnt lgkmcnt(0)
	v_mfma_f32_16x16x32_bf16 v[126:129], v[150:153], v[170:173], v[126:129]
	v_mfma_f32_16x16x32_bf16 v[122:125], v[162:165], v[170:173], v[122:125]
	v_mfma_f32_16x16x32_bf16 v[110:113], v[150:153], v[178:181], v[110:113]
	v_mfma_f32_16x16x32_bf16 v[106:109], v[162:165], v[178:181], v[106:109]
	v_mfma_f32_16x16x32_bf16 v[94:97], v[150:153], v[186:189], v[94:97]
	v_mfma_f32_16x16x32_bf16 v[90:93], v[162:165], v[186:189], v[90:93]
	v_mfma_f32_16x16x32_bf16 v[78:81], v[150:153], v[194:197], v[78:81]
	v_mfma_f32_16x16x32_bf16 v[74:77], v[162:165], v[194:197], v[74:77]
	v_mfma_f32_16x16x32_bf16 v[126:129], v[154:157], v[174:177], v[126:129]
	v_mfma_f32_16x16x32_bf16 v[122:125], v[166:169], v[174:177], v[122:125]
	v_mfma_f32_16x16x32_bf16 v[110:113], v[154:157], v[182:185], v[110:113]
	v_mfma_f32_16x16x32_bf16 v[106:109], v[166:169], v[182:185], v[106:109]
	v_mfma_f32_16x16x32_bf16 v[94:97], v[154:157], v[190:193], v[94:97]
	v_mfma_f32_16x16x32_bf16 v[90:93], v[166:169], v[190:193], v[90:93]
	v_mfma_f32_16x16x32_bf16 v[78:81], v[154:157], v[198:201], v[78:81]
	v_mfma_f32_16x16x32_bf16 v[74:77], v[166:169], v[198:201], v[74:77]
	s_setprio 0
	s_barrier
	s_add_i32 s51, s43, s29
	v_lshl_add_u64 v[218:219], s[22:23], 0, v[134:135]
	s_mov_b32 m0, s51
	ds_read_b128 v[202:205], v161
	ds_read_b128 v[206:209], v161 offset:1024
	ds_read_b128 v[210:213], v161 offset:2048
	ds_read_b128 v[214:217], v161 offset:3072
	global_load_lds_dwordx4 v[218:219], off
	v_lshl_add_u64 v[220:221], s[22:23], 0, v[138:139]
	s_add_i32 m0, s51, 0x2000
	s_nop 0
	global_load_lds_dwordx4 v[220:221], off
	s_barrier
	s_waitcnt lgkmcnt(0)
	s_setprio 1
	s_waitcnt lgkmcnt(0)
	v_mfma_f32_16x16x32_bf16 v[118:121], v[202:205], v[170:173], v[118:121]
	v_mfma_f32_16x16x32_bf16 v[114:117], v[210:213], v[170:173], v[114:117]
	v_mfma_f32_16x16x32_bf16 v[102:105], v[202:205], v[178:181], v[102:105]
	v_mfma_f32_16x16x32_bf16 v[98:101], v[210:213], v[178:181], v[98:101]
	v_mfma_f32_16x16x32_bf16 v[86:89], v[202:205], v[186:189], v[86:89]
	v_mfma_f32_16x16x32_bf16 v[82:85], v[210:213], v[186:189], v[82:85]
	v_mfma_f32_16x16x32_bf16 v[70:73], v[202:205], v[194:197], v[70:73]
	v_mfma_f32_16x16x32_bf16 v[66:69], v[210:213], v[194:197], v[66:69]
	v_mfma_f32_16x16x32_bf16 v[118:121], v[206:209], v[174:177], v[118:121]
	v_mfma_f32_16x16x32_bf16 v[114:117], v[214:217], v[174:177], v[114:117]
	v_mfma_f32_16x16x32_bf16 v[102:105], v[206:209], v[182:185], v[102:105]
	v_mfma_f32_16x16x32_bf16 v[98:101], v[214:217], v[182:185], v[98:101]
	v_mfma_f32_16x16x32_bf16 v[86:89], v[206:209], v[190:193], v[86:89]
	v_mfma_f32_16x16x32_bf16 v[82:85], v[214:217], v[190:193], v[82:85]
	v_mfma_f32_16x16x32_bf16 v[70:73], v[206:209], v[198:201], v[70:73]
	v_mfma_f32_16x16x32_bf16 v[66:69], v[214:217], v[198:201], v[66:69]
	s_setprio 0
	s_mov_b32 m0, s30
	v_lshl_add_u64 v[222:223], s[24:25], 0, v[132:133]
	s_barrier
	ds_read_b128 v[170:173], v160 offset:16384
	ds_read_b128 v[174:177], v160 offset:17408
	ds_read_b128 v[178:181], v160 offset:18432
	ds_read_b128 v[182:185], v160 offset:19456
	ds_read_b128 v[186:189], v160 offset:20480
	ds_read_b128 v[190:193], v160 offset:21504
	ds_read_b128 v[194:197], v160 offset:22528
	ds_read_b128 v[198:201], v160 offset:23552
	global_load_lds_dwordx4 v[222:223], off
	v_lshl_add_u64 v[224:225], s[24:25], 0, v[136:137]
	s_mov_b32 m0, s31
	s_nop 0
	global_load_lds_dwordx4 v[224:225], off
	s_barrier
	s_waitcnt lgkmcnt(0)
	s_setprio 1
	s_waitcnt lgkmcnt(0)
	v_mfma_f32_16x16x32_bf16 v[62:65], v[150:153], v[170:173], v[62:65]
	v_mfma_f32_16x16x32_bf16 v[58:61], v[162:165], v[170:173], v[58:61]
	v_mfma_f32_16x16x32_bf16 v[46:49], v[150:153], v[178:181], v[46:49]
	v_mfma_f32_16x16x32_bf16 v[42:45], v[162:165], v[178:181], v[42:45]
	v_mfma_f32_16x16x32_bf16 v[30:33], v[150:153], v[186:189], v[30:33]
	v_mfma_f32_16x16x32_bf16 v[26:29], v[162:165], v[186:189], v[26:29]
	v_mfma_f32_16x16x32_bf16 v[14:17], v[150:153], v[194:197], v[14:17]
	v_mfma_f32_16x16x32_bf16 v[10:13], v[162:165], v[194:197], v[10:13]
	v_mfma_f32_16x16x32_bf16 v[62:65], v[154:157], v[174:177], v[62:65]
	v_mfma_f32_16x16x32_bf16 v[58:61], v[166:169], v[174:177], v[58:61]
	v_mfma_f32_16x16x32_bf16 v[46:49], v[154:157], v[182:185], v[46:49]
	v_mfma_f32_16x16x32_bf16 v[42:45], v[166:169], v[182:185], v[42:45]
	v_mfma_f32_16x16x32_bf16 v[30:33], v[154:157], v[190:193], v[30:33]
	v_mfma_f32_16x16x32_bf16 v[26:29], v[166:169], v[190:193], v[26:29]
	v_mfma_f32_16x16x32_bf16 v[14:17], v[154:157], v[198:201], v[14:17]
	v_mfma_f32_16x16x32_bf16 v[10:13], v[166:169], v[198:201], v[10:13]
	s_setprio 0
	s_barrier
; #define PG8_STAGE(bufoff, gbase, voff) do { _Pragma("unroll") for (int _i = 0; _i < 2; ++_i) \
;         __builtin_amdgcn_global_load_lds((const unsigned*)((const char*)(gbase) + (voff)[_i]), (PG8_LAS unsigned*)(lds + (bufoff) + ldsw + _i * 8192), 16, 0, 0); } while (0)
; #define PG8_LDA(dst, b, h) do { _Pragma("unroll") for (int m = 0; m < 4; ++m) _Pragma("unroll") for (int k = 0; k < 2; ++k) dst[m][k] = *(const PG8_LAS bf16x8*)(lds + PG8_SA(b, h) + aoff + m * 2048 + k * 1024); } while (0)
; #define PG8_LDB(dst, b, h) do { _Pragma("unroll") for (int n = 0; n < 2; ++n) _Pragma("unroll") for (int k = 0; k < 2; ++k) dst[n][k] = *(const PG8_LAS bf16x8*)(lds + PG8_SB(b, h) + boff + n * 2048 + k * 1024); } while (0)
; #define PG8_MMA(ai, bj, At, Bt) do { __builtin_amdgcn_s_setprio(1); _Pragma("unroll") for (int m = 0; m < 4; ++m) _Pragma("unroll") for (int n = 0; n < 2; ++n) _Pragma("unroll") for (int k = 0; k < 2; ++k) \
;         acc[ai][bj][m][n] = __builtin_amdgcn_mfma_f32_16x16x32_bf16(Bt[n][k], At[m][k], acc[ai][bj][m][n], 0, 0, 0); __builtin_amdgcn_s_setprio(0); } while (0)
; #define PG8_WAIT_V(n) asm volatile("s_waitcnt vmcnt(" #n ")" ::: "memory")
; #define PG8_WAIT_L(n) asm volatile("s_waitcnt lgkmcnt(" #n ")" ::: "memory")
; #define PG8_BAR __builtin_amdgcn_s_barrier()
; #define PG8_SCHED __builtin_amdgcn_sched_barrier(0)
; template <class Epi>
; __device__ __forceinline__ void gemm_phase(PG8_LAS unsigned char* lds, const Gemm g, const StaticOrder& S, const Epi& E) {
;     ...
;             PG8_STAGE(PG8_SB(0, 1), b2 + hstep, voffB);
;             PG8_WAIT_V(6); PG8_BAR; PG8_MMA(1, 1, At, B1); PG8_BAR;
;             PG8_LDB(B0, 1, 0); PG8_SCHED; PG8_LDA(At, 1, 0); PG8_STAGE(PG8_SA(0, 1), a2 + hstep, voffA);
;             PG8_WAIT_L(8); PG8_BAR; PG8_WAIT_L(0); PG8_MMA(0, 0, At, B0); PG8_BAR; PG8_SCHED;
;             PG8_LDB(B1, 1, 1); PG8_STAGE(PG8_SB(1, 0), b3, voffB);
;             PG8_BAR; PG8_WAIT_L(0); PG8_MMA(0, 1, At, B1); PG8_BAR;
;             PG8_LDA(At, 1, 1); PG8_STAGE(PG8_SA(1, 0), a3, voffA);
;             PG8_BAR; PG8_WAIT_L(0); PG8_MMA(1, 0, At, B0); PG8_BAR; PG8_SCHED;
	s_add_u32 s52, s22, 0x80000
	s_addc_u32 s53, s23, 0
	s_add_i32 s51, s44, s29
	v_lshl_add_u64 v[150:151], s[52:53], 0, v[134:135]
	s_mov_b32 m0, s51
	s_nop 0
	global_load_lds_dwordx4 v[150:151], off
	v_lshl_add_u64 v[150:151], s[52:53], 0, v[138:139]
	s_add_i32 m0, s51, 0x2000
	s_nop 0
	global_load_lds_dwordx4 v[150:151], off
	s_waitcnt vmcnt(6)
	s_barrier
	s_setprio 1
	v_mfma_f32_16x16x32_bf16 v[54:57], v[202:205], v[170:173], v[54:57]
	v_mfma_f32_16x16x32_bf16 v[50:53], v[210:213], v[170:173], v[50:53]
	v_mfma_f32_16x16x32_bf16 v[38:41], v[202:205], v[178:181], v[38:41]
	v_mfma_f32_16x16x32_bf16 v[34:37], v[210:213], v[178:181], v[34:37]
	v_mfma_f32_16x16x32_bf16 v[22:25], v[202:205], v[186:189], v[22:25]
	v_mfma_f32_16x16x32_bf16 v[18:21], v[210:213], v[186:189], v[18:21]
	v_mfma_f32_16x16x32_bf16 v[6:9], v[202:205], v[194:197], v[6:9]
	v_mfma_f32_16x16x32_bf16 v[2:5], v[210:213], v[194:197], v[2:5]
	v_mfma_f32_16x16x32_bf16 v[54:57], v[206:209], v[174:177], v[54:57]
	v_mfma_f32_16x16x32_bf16 v[50:53], v[214:217], v[174:177], v[50:53]
	v_mfma_f32_16x16x32_bf16 v[38:41], v[206:209], v[182:185], v[38:41]
	v_mfma_f32_16x16x32_bf16 v[34:37], v[214:217], v[182:185], v[34:37]
	v_mfma_f32_16x16x32_bf16 v[22:25], v[206:209], v[190:193], v[22:25]
	v_mfma_f32_16x16x32_bf16 v[18:21], v[214:217], v[190:193], v[18:21]
	v_mfma_f32_16x16x32_bf16 v[6:9], v[206:209], v[198:201], v[6:9]
	v_mfma_f32_16x16x32_bf16 v[2:5], v[214:217], v[198:201], v[2:5]
	s_setprio 0
	s_add_i32 s51, 0, 0x18000
	v_add_u32_e32 v140, s51, v131
	s_barrier
	ds_read_b128 v[150:153], v140
	ds_read_b128 v[154:157], v140 offset:1024
	ds_read_b128 v[162:165], v140 offset:2048
	ds_read_b128 v[166:169], v140 offset:3072
	s_add_u32 s24, s24, 0x80000
	s_addc_u32 s25, s25, 0
	s_mov_b32 m0, s33
	v_lshl_add_u64 v[202:203], s[24:25], 0, v[132:133]
	ds_read_b128 v[170:173], v160 offset:32768
	ds_read_b128 v[174:177], v160 offset:33792
	ds_read_b128 v[178:181], v160 offset:34816
	ds_read_b128 v[182:185], v160 offset:35840
	ds_read_b128 v[186:189], v160 offset:36864
	ds_read_b128 v[190:193], v160 offset:37888
	ds_read_b128 v[194:197], v160 offset:38912
	ds_read_b128 v[198:201], v160 offset:39936
	global_load_lds_dwordx4 v[202:203], off
	v_lshl_add_u64 v[202:203], s[24:25], 0, v[136:137]
	s_mov_b32 m0, s34
	s_nop 0
	global_load_lds_dwordx4 v[202:203], off
	s_waitcnt lgkmcnt(8)
	s_barrier
	s_waitcnt lgkmcnt(0)
	s_setprio 1
	s_waitcnt lgkmcnt(0)
	v_mfma_f32_16x16x32_bf16 v[126:129], v[150:153], v[170:173], v[126:129]
	v_mfma_f32_16x16x32_bf16 v[122:125], v[162:165], v[170:173], v[122:125]
	v_mfma_f32_16x16x32_bf16 v[110:113], v[150:153], v[178:181], v[110:113]
	v_mfma_f32_16x16x32_bf16 v[106:109], v[162:165], v[178:181], v[106:109]
	v_mfma_f32_16x16x32_bf16 v[94:97], v[150:153], v[186:189], v[94:97]
	v_mfma_f32_16x16x32_bf16 v[90:93], v[162:165], v[186:189], v[90:93]
	v_mfma_f32_16x16x32_bf16 v[78:81], v[150:153], v[194:197], v[78:81]
	v_mfma_f32_16x16x32_bf16 v[74:77], v[162:165], v[194:197], v[74:77]
	v_mfma_f32_16x16x32_bf16 v[126:129], v[154:157], v[174:177], v[126:129]
	v_mfma_f32_16x16x32_bf16 v[122:125], v[166:169], v[174:177], v[122:125]
	v_mfma_f32_16x16x32_bf16 v[110:113], v[154:157], v[182:185], v[110:113]
	v_mfma_f32_16x16x32_bf16 v[106:109], v[166:169], v[182:185], v[106:109]
	v_mfma_f32_16x16x32_bf16 v[94:97], v[154:157], v[190:193], v[94:97]
	v_mfma_f32_16x16x32_bf16 v[90:93], v[166:169], v[190:193], v[90:93]
	v_mfma_f32_16x16x32_bf16 v[78:81], v[154:157], v[198:201], v[78:81]
	v_mfma_f32_16x16x32_bf16 v[74:77], v[166:169], v[198:201], v[74:77]
	s_setprio 0
	s_barrier
	s_add_i32 s24, 0, 0x1c000
	s_add_i32 s25, s51, s29
	v_add_u32_e32 v140, s24, v131
	v_lshl_add_u64 v[218:219], v[218:219], 0, s[10:11]
	s_mov_b32 m0, s25
	ds_read_b128 v[202:205], v140
	ds_read_b128 v[206:209], v140 offset:1024
	ds_read_b128 v[210:213], v140 offset:2048
	ds_read_b128 v[214:217], v140 offset:3072
	global_load_lds_dwordx4 v[218:219], off
	v_lshl_add_u64 v[218:219], v[220:221], 0, s[10:11]
	s_add_i32 m0, s25, 0x2000
	s_nop 0
	global_load_lds_dwordx4 v[218:219], off
	s_barrier
	s_waitcnt lgkmcnt(0)
	s_setprio 1
	s_waitcnt lgkmcnt(0)
	v_mfma_f32_16x16x32_bf16 v[118:121], v[202:205], v[170:173], v[118:121]
	v_mfma_f32_16x16x32_bf16 v[114:117], v[210:213], v[170:173], v[114:117]
	v_mfma_f32_16x16x32_bf16 v[102:105], v[202:205], v[178:181], v[102:105]
	v_mfma_f32_16x16x32_bf16 v[98:101], v[210:213], v[178:181], v[98:101]
	v_mfma_f32_16x16x32_bf16 v[86:89], v[202:205], v[186:189], v[86:89]
	v_mfma_f32_16x16x32_bf16 v[82:85], v[210:213], v[186:189], v[82:85]
	v_mfma_f32_16x16x32_bf16 v[70:73], v[202:205], v[194:197], v[70:73]
	v_mfma_f32_16x16x32_bf16 v[66:69], v[210:213], v[194:197], v[66:69]
	v_mfma_f32_16x16x32_bf16 v[118:121], v[206:209], v[174:177], v[118:121]
	v_mfma_f32_16x16x32_bf16 v[114:117], v[214:217], v[174:177], v[114:117]
	v_mfma_f32_16x16x32_bf16 v[102:105], v[206:209], v[182:185], v[102:105]
	v_mfma_f32_16x16x32_bf16 v[98:101], v[214:217], v[182:185], v[98:101]
	v_mfma_f32_16x16x32_bf16 v[86:89], v[206:209], v[190:193], v[86:89]
	v_mfma_f32_16x16x32_bf16 v[82:85], v[214:217], v[190:193], v[82:85]
	v_mfma_f32_16x16x32_bf16 v[70:73], v[206:209], v[198:201], v[70:73]
	v_mfma_f32_16x16x32_bf16 v[66:69], v[214:217], v[198:201], v[66:69]
	s_setprio 0
	s_mov_b32 m0, s38
	v_lshl_add_u64 v[218:219], v[222:223], 0, s[10:11]
	s_barrier
; #define PG8_STAGE(bufoff, gbase, voff) do { _Pragma("unroll") for (int _i = 0; _i < 2; ++_i) \
;         __builtin_amdgcn_global_load_lds((const unsigned*)((const char*)(gbase) + (voff)[_i]), (PG8_LAS unsigned*)(lds + (bufoff) + ldsw + _i * 8192), 16, 0, 0); } while (0)
; #define PG8_MMA(ai, bj, At, Bt) do { __builtin_amdgcn_s_setprio(1); _Pragma("unroll") for (int m = 0; m < 4; ++m) _Pragma("unroll") for (int n = 0; n < 2; ++n) _Pragma("unroll") for (int k = 0; k < 2; ++k) \
;         acc[ai][bj][m][n] = __builtin_amdgcn_mfma_f32_16x16x32_bf16(Bt[n][k], At[m][k], acc[ai][bj][m][n], 0, 0, 0); __builtin_amdgcn_s_setprio(0); } while (0)
; #define PG8_WAIT_V(n) asm volatile("s_waitcnt vmcnt(" #n ")" ::: "memory")
; #define PG8_WAIT_L(n) asm volatile("s_waitcnt lgkmcnt(" #n ")" ::: "memory")
; #define PG8_BAR __builtin_amdgcn_s_barrier()
; #define PG8_SCHED __builtin_amdgcn_sched_barrier(0)
; template <class Epi>
; __device__ __forceinline__ void gemm_phase(PG8_LAS unsigned char* lds, const Gemm g, const StaticOrder& S, const Epi& E) {
;     ...
;             PG8_BAR; PG8_WAIT_L(0); PG8_MMA(1, 0, At, B0); PG8_BAR; PG8_SCHED;
;             PG8_STAGE(PG8_SB(1, 1), b3 + hstep, voffB);
;             PG8_WAIT_V(6); PG8_BAR; PG8_MMA(1, 1, At, B1); PG8_BAR;
;         }
;         E(acc, cur, wr, wc, fr, fq);
	ds_read_b128 v[170:173], v160 offset:49152
	ds_read_b128 v[174:177], v160 offset:50176
	ds_read_b128 v[178:181], v160 offset:51200
	ds_read_b128 v[182:185], v160 offset:52224
	ds_read_b128 v[186:189], v160 offset:53248
	ds_read_b128 v[190:193], v160 offset:54272
	ds_read_b128 v[194:197], v160 offset:55296
	ds_read_b128 v[198:201], v160 offset:56320
	global_load_lds_dwordx4 v[218:219], off
	v_lshl_add_u64 v[218:219], v[224:225], 0, s[10:11]
	s_mov_b32 m0, s39
	s_nop 0
	global_load_lds_dwordx4 v[218:219], off
	s_barrier
	s_waitcnt lgkmcnt(0)
	s_setprio 1
	s_waitcnt lgkmcnt(0)
	v_mfma_f32_16x16x32_bf16 v[62:65], v[150:153], v[170:173], v[62:65]
	v_mfma_f32_16x16x32_bf16 v[58:61], v[162:165], v[170:173], v[58:61]
	v_mfma_f32_16x16x32_bf16 v[46:49], v[150:153], v[178:181], v[46:49]
	v_mfma_f32_16x16x32_bf16 v[42:45], v[162:165], v[178:181], v[42:45]
	v_mfma_f32_16x16x32_bf16 v[30:33], v[150:153], v[186:189], v[30:33]
	v_mfma_f32_16x16x32_bf16 v[26:29], v[162:165], v[186:189], v[26:29]
	v_mfma_f32_16x16x32_bf16 v[14:17], v[150:153], v[194:197], v[14:17]
	v_mfma_f32_16x16x32_bf16 v[10:13], v[162:165], v[194:197], v[10:13]
	v_mfma_f32_16x16x32_bf16 v[62:65], v[154:157], v[174:177], v[62:65]
	v_mfma_f32_16x16x32_bf16 v[58:61], v[166:169], v[174:177], v[58:61]
	v_mfma_f32_16x16x32_bf16 v[46:49], v[154:157], v[182:185], v[46:49]
	v_mfma_f32_16x16x32_bf16 v[42:45], v[166:169], v[182:185], v[42:45]
	v_mfma_f32_16x16x32_bf16 v[30:33], v[154:157], v[190:193], v[30:33]
	v_mfma_f32_16x16x32_bf16 v[26:29], v[166:169], v[190:193], v[26:29]
	v_mfma_f32_16x16x32_bf16 v[14:17], v[154:157], v[198:201], v[14:17]
	v_mfma_f32_16x16x32_bf16 v[10:13], v[166:169], v[198:201], v[10:13]
	s_setprio 0
	s_barrier
	s_add_u32 s22, s22, 0x80080
	s_addc_u32 s23, s23, 0
	s_add_i32 s24, s24, s29
	v_lshl_add_u64 v[150:151], s[22:23], 0, v[134:135]
	s_mov_b32 m0, s24
	s_nop 0
	global_load_lds_dwordx4 v[150:151], off
	v_lshl_add_u64 v[150:151], s[22:23], 0, v[138:139]
	s_add_i32 m0, s24, 0x2000
	s_nop 0
	global_load_lds_dwordx4 v[150:151], off
	s_waitcnt vmcnt(6)
	s_barrier
	s_setprio 1
	v_mfma_f32_16x16x32_bf16 v[54:57], v[202:205], v[170:173], v[54:57]
	v_mfma_f32_16x16x32_bf16 v[50:53], v[210:213], v[170:173], v[50:53]
	v_mfma_f32_16x16x32_bf16 v[38:41], v[202:205], v[178:181], v[38:41]
	v_mfma_f32_16x16x32_bf16 v[34:37], v[210:213], v[178:181], v[34:37]
	v_mfma_f32_16x16x32_bf16 v[22:25], v[202:205], v[186:189], v[22:25]
	v_mfma_f32_16x16x32_bf16 v[18:21], v[210:213], v[186:189], v[18:21]
	v_mfma_f32_16x16x32_bf16 v[6:9], v[202:205], v[194:197], v[6:9]
	v_mfma_f32_16x16x32_bf16 v[2:5], v[210:213], v[194:197], v[2:5]
	v_mfma_f32_16x16x32_bf16 v[54:57], v[206:209], v[174:177], v[54:57]
	v_mfma_f32_16x16x32_bf16 v[50:53], v[214:217], v[174:177], v[50:53]
	v_mfma_f32_16x16x32_bf16 v[38:41], v[206:209], v[182:185], v[38:41]
	v_mfma_f32_16x16x32_bf16 v[34:37], v[214:217], v[182:185], v[34:37]
	v_mfma_f32_16x16x32_bf16 v[22:25], v[206:209], v[190:193], v[22:25]
	v_mfma_f32_16x16x32_bf16 v[18:21], v[214:217], v[190:193], v[18:21]
	v_mfma_f32_16x16x32_bf16 v[6:9], v[206:209], v[198:201], v[6:9]
	v_mfma_f32_16x16x32_bf16 v[2:5], v[214:217], v[198:201], v[2:5]
	s_setprio 0
	s_add_i32 s50, s50, 2
	s_add_u32 s20, s20, 0x100
	s_addc_u32 s21, s21, 0
	s_add_u32 s48, s48, 0x100
	s_addc_u32 s49, s49, 0
	s_cmp_gt_u32 s50, 29
	s_barrier
	s_cbranch_scc0 .LBB0_722
	v_lshl_add_u32 v152, s2, 8, v1
	s_lshl_b32 s13, s4, 8
	v_or_b32_e32 v150, s13, v158
	v_mad_i64_i32 v[154:155], s[2:3], v152, s45, 0
	v_cmp_lt_i32_e64 s[2:3], s46, v150
	s_and_saveexec_b64 s[20:21], s[2:3]
	s_xor_b64 s[20:21], exec, s[20:21]
	s_cbranch_execz .LBB0_726
	s_cmpk_gt_u32 s13, 0x317f
	s_cbranch_scc1 .LBB0_726
	v_lshl_add_u64 v[156:157], s[8:9], 0, v[154:155]
	v_mov_b32_e32 v151, v141
	v_lshl_add_u64 v[156:157], v[150:151], 1, v[156:157]
	v_add_co_u32_e32 v156, vcc, 0xffffa000, v156
	v_cvt_pk_bf16_f32 v162, v126, v127
	v_cvt_pk_bf16_f32 v163, v128, v129
	v_cvt_pk_bf16_f32 v164, v122, v123
	v_cvt_pk_bf16_f32 v165, v124, v125
	s_nop 1
	v_addc_co_u32_e32 v157, vcc, -1, v157, vcc
	global_store_dwordx4 v[156:157], v[162:165], off nt
.LBB0_726:
	s_or_saveexec_b64 s[22:23], s[20:21]
	s_ashr_i32 s4, s4, 4
	s_ashr_i32 s5, s4, 31
	v_ashrrev_i32_e32 v153, 31, v152
	s_lshl_b64 s[20:21], s[4:5], 27
	v_lshlrev_b64 v[156:157], 13, v[152:153]
	s_xor_b64 exec, exec, s[22:23]
	s_cbranch_execz .LBB0_728
	s_add_u32 s4, s36, s20
	v_and_b32_e32 v140, 0xf78, v150
	s_addc_u32 s5, s37, s21
	v_lshl_add_u64 v[162:163], s[4:5], 0, v[156:157]
	v_lshlrev_b32_e32 v140, 1, v140
	v_lshl_add_u64 v[162:163], v[162:163], 0, v[140:141]
	v_cvt_pk_bf16_f32 v126, v126, v127
	v_cvt_pk_bf16_f32 v127, v128, v129
	v_cvt_pk_bf16_f32 v128, v122, v123
	v_cvt_pk_bf16_f32 v129, v124, v125
	global_store_dwordx4 v[162:163], v[126:129], off nt
.LBB0_728:
	s_or_b64 exec, exec, s[22:23]
	v_or_b32_e32 v122, 0x80, v150
	v_cmp_lt_i32_e64 s[4:5], s46, v122
	s_and_saveexec_b64 s[22:23], s[4:5]
	s_xor_b64 s[22:23], exec, s[22:23]
	s_cbranch_execz .LBB0_732
	v_cmp_gt_u32_e32 vcc, s47, v122
	s_and_saveexec_b64 s[24:25], vcc
	s_cbranch_execz .LBB0_731
	v_lshl_add_u64 v[124:125], s[8:9], 0, v[154:155]
	v_mov_b32_e32 v151, v141
	v_lshl_add_u64 v[128:129], v[150:151], 1, v[124:125]
	v_add_co_u32_e32 v128, vcc, 0xffffb000, v128
	v_cvt_pk_bf16_f32 v124, v118, v119
	v_cvt_pk_bf16_f32 v125, v120, v121
	v_cvt_pk_bf16_f32 v126, v114, v115
	v_cvt_pk_bf16_f32 v127, v116, v117
	s_nop 1
	v_addc_co_u32_e32 v129, vcc, -1, v129, vcc
	global_store_dwordx4 v[128:129], v[124:127], off offset:-3840 nt

; __device__ __forceinline__ unsigned pk2(float lo, float hi) { unsigned r; asm volatile("v_cvt_pk_bf16_f32 %0, %1, %2" : "=v"(r) : "v"(lo), "v"(hi)); return r; }
; __device__ __forceinline__ void store8bf(u16* dst, f32x4 v0, f32x4 v1) { u32x4 w; w.x = pk2(v0[0], v0[1]); w.y = pk2(v0[2], v0[3]); w.z = pk2(v1[0], v1[1]); w.w = pk2(v1[2], v1[3]); *(u32x4*)dst = w; }
.LBB0_732:
	s_andn2_saveexec_b64 s[22:23], s[22:23]
	s_cbranch_execz .LBB0_734
	s_add_u32 s24, s36, s20
	v_and_b32_e32 v123, 0xff8, v122
	s_addc_u32 s25, s37, s21
	v_lshl_add_u64 v[124:125], s[24:25], 0, v[156:157]
	v_lshlrev_b32_e32 v140, 1, v123
	v_lshl_add_u64 v[124:125], v[124:125], 0, v[140:141]
	v_cvt_pk_bf16_f32 v118, v118, v119
	v_cvt_pk_bf16_f32 v119, v120, v121
	v_cvt_pk_bf16_f32 v120, v114, v115
	v_cvt_pk_bf16_f32 v121, v116, v117
	global_store_dwordx4 v[124:125], v[118:121], off nt
.LBB0_734:
	s_or_b64 exec, exec, s[22:23]
	v_or_b32_e32 v116, 16, v152
	v_mad_i64_i32 v[114:115], s[22:23], v116, s45, 0
	s_and_saveexec_b64 s[22:23], s[2:3]
	s_xor_b64 s[22:23], exec, s[22:23]
	s_cbranch_execz .LBB0_737
	s_cmpk_gt_u32 s13, 0x317f
	s_cbranch_scc1 .LBB0_737
	v_lshl_add_u64 v[118:119], s[8:9], 0, v[114:115]
	v_mov_b32_e32 v151, v141
	v_lshl_add_u64 v[124:125], v[150:151], 1, v[118:119]
	v_add_co_u32_e32 v124, vcc, 0xffffa000, v124
	v_cvt_pk_bf16_f32 v118, v110, v111
	v_cvt_pk_bf16_f32 v119, v112, v113
	v_cvt_pk_bf16_f32 v120, v106, v107
	v_cvt_pk_bf16_f32 v121, v108, v109
	s_nop 1
	v_addc_co_u32_e32 v125, vcc, -1, v125, vcc
	global_store_dwordx4 v[124:125], v[118:121], off nt

; __device__ __forceinline__ unsigned pk2(float lo, float hi) { unsigned r; asm volatile("v_cvt_pk_bf16_f32 %0, %1, %2" : "=v"(r) : "v"(lo), "v"(hi)); return r; }
; __device__ __forceinline__ void store8bf(u16* dst, f32x4 v0, f32x4 v1) { u32x4 w; w.x = pk2(v0[0], v0[1]); w.y = pk2(v0[2], v0[3]); w.z = pk2(v1[0], v1[1]); w.w = pk2(v1[2], v1[3]); *(u32x4*)dst = w; }
.LBB0_740:
	s_add_u32 s24, s36, s20
	v_and_b32_e32 v108, 0xff8, v122
	s_addc_u32 s25, s37, s21
	v_lshl_add_u64 v[106:107], s[24:25], 0, v[116:117]
	v_lshlrev_b32_e32 v140, 1, v108
	v_lshl_add_u64 v[106:107], v[106:107], 0, v[140:141]
	v_cvt_pk_bf16_f32 v102, v102, v103
	v_cvt_pk_bf16_f32 v103, v104, v105
	v_cvt_pk_bf16_f32 v104, v98, v99
	v_cvt_pk_bf16_f32 v105, v100, v101
	global_store_dwordx4 v[106:107], v[102:105], off nt
.LBB0_741:
	s_or_b64 exec, exec, s[22:23]
	v_or_b32_e32 v100, 32, v152
	v_mad_i64_i32 v[98:99], s[22:23], v100, s45, 0
	s_and_saveexec_b64 s[22:23], s[2:3]
	s_xor_b64 s[22:23], exec, s[22:23]
	s_cbranch_execz .LBB0_744
	s_cmpk_gt_u32 s13, 0x317f
	s_cbranch_scc1 .LBB0_744
	v_lshl_add_u64 v[102:103], s[8:9], 0, v[98:99]
	v_mov_b32_e32 v151, v141
	v_lshl_add_u64 v[106:107], v[150:151], 1, v[102:103]
	v_add_co_u32_e32 v106, vcc, 0xffffa000, v106
	v_cvt_pk_bf16_f32 v102, v94, v95
	v_cvt_pk_bf16_f32 v103, v96, v97
	v_cvt_pk_bf16_f32 v104, v90, v91
	v_cvt_pk_bf16_f32 v105, v92, v93
	s_nop 1
	v_addc_co_u32_e32 v107, vcc, -1, v107, vcc
	global_store_dwordx4 v[106:107], v[102:105], off nt

; __device__ __forceinline__ unsigned pk2(float lo, float hi) { unsigned r; asm volatile("v_cvt_pk_bf16_f32 %0, %1, %2" : "=v"(r) : "v"(lo), "v"(hi)); return r; }
; __device__ __forceinline__ void store8bf(u16* dst, f32x4 v0, f32x4 v1) { u32x4 w; w.x = pk2(v0[0], v0[1]); w.y = pk2(v0[2], v0[3]); w.z = pk2(v1[0], v1[1]); w.w = pk2(v1[2], v1[3]); *(u32x4*)dst = w; }
.LBB0_747:
	s_add_u32 s24, s36, s20
	v_and_b32_e32 v92, 0xff8, v122
	s_addc_u32 s25, s37, s21
	v_lshl_add_u64 v[90:91], s[24:25], 0, v[100:101]
	v_lshlrev_b32_e32 v140, 1, v92
	v_lshl_add_u64 v[90:91], v[90:91], 0, v[140:141]
	v_cvt_pk_bf16_f32 v86, v86, v87
	v_cvt_pk_bf16_f32 v87, v88, v89
	v_cvt_pk_bf16_f32 v88, v82, v83
	v_cvt_pk_bf16_f32 v89, v84, v85
	global_store_dwordx4 v[90:91], v[86:89], off nt
.LBB0_748:
	s_or_b64 exec, exec, s[22:23]
	v_or_b32_e32 v84, 48, v152
	v_mad_i64_i32 v[82:83], s[22:23], v84, s45, 0
	s_and_saveexec_b64 s[22:23], s[2:3]
	s_xor_b64 s[22:23], exec, s[22:23]
	s_cbranch_execz .LBB0_751
	s_cmpk_gt_u32 s13, 0x317f
	s_cbranch_scc1 .LBB0_751
	v_lshl_add_u64 v[86:87], s[8:9], 0, v[82:83]
	v_mov_b32_e32 v151, v141
	v_lshl_add_u64 v[90:91], v[150:151], 1, v[86:87]
	v_add_co_u32_e32 v90, vcc, 0xffffa000, v90
	v_cvt_pk_bf16_f32 v86, v78, v79
	v_cvt_pk_bf16_f32 v87, v80, v81
	v_cvt_pk_bf16_f32 v88, v74, v75
	v_cvt_pk_bf16_f32 v89, v76, v77
	s_nop 1
	v_addc_co_u32_e32 v91, vcc, -1, v91, vcc
	global_store_dwordx4 v[90:91], v[86:89], off nt

; __device__ __forceinline__ unsigned pk2(float lo, float hi) { unsigned r; asm volatile("v_cvt_pk_bf16_f32 %0, %1, %2" : "=v"(r) : "v"(lo), "v"(hi)); return r; }
; __device__ __forceinline__ void store8bf(u16* dst, f32x4 v0, f32x4 v1) { u32x4 w; w.x = pk2(v0[0], v0[1]); w.y = pk2(v0[2], v0[3]); w.z = pk2(v1[0], v1[1]); w.w = pk2(v1[2], v1[3]); *(u32x4*)dst = w; }
.LBB0_754:
	s_add_u32 s24, s36, s20
	v_and_b32_e32 v76, 0xff8, v122
	s_addc_u32 s25, s37, s21
	v_lshl_add_u64 v[74:75], s[24:25], 0, v[84:85]
	v_lshlrev_b32_e32 v140, 1, v76
	v_lshl_add_u64 v[74:75], v[74:75], 0, v[140:141]
	v_cvt_pk_bf16_f32 v70, v70, v71
	v_cvt_pk_bf16_f32 v71, v72, v73
	v_cvt_pk_bf16_f32 v72, v66, v67
	v_cvt_pk_bf16_f32 v73, v68, v69
	global_store_dwordx4 v[74:75], v[70:73], off nt
.LBB0_755:
	s_or_b64 exec, exec, s[22:23]
	v_add_u32_e32 v68, 0x80, v152
	v_mad_i64_i32 v[66:67], s[22:23], v68, s45, 0
	s_and_saveexec_b64 s[22:23], s[2:3]
	s_xor_b64 s[22:23], exec, s[22:23]
	s_cbranch_execz .LBB0_758
	s_cmpk_gt_u32 s13, 0x317f
	s_cbranch_scc1 .LBB0_758
	v_lshl_add_u64 v[70:71], s[8:9], 0, v[66:67]
	v_mov_b32_e32 v151, v141
	v_lshl_add_u64 v[74:75], v[150:151], 1, v[70:71]
	v_add_co_u32_e32 v74, vcc, 0xffffa000, v74
	v_cvt_pk_bf16_f32 v70, v62, v63
	v_cvt_pk_bf16_f32 v71, v64, v65
	v_cvt_pk_bf16_f32 v72, v58, v59
	v_cvt_pk_bf16_f32 v73, v60, v61
	s_nop 1
	v_addc_co_u32_e32 v75, vcc, -1, v75, vcc
	global_store_dwordx4 v[74:75], v[70:73], off nt

; __device__ __forceinline__ unsigned pk2(float lo, float hi) { unsigned r; asm volatile("v_cvt_pk_bf16_f32 %0, %1, %2" : "=v"(r) : "v"(lo), "v"(hi)); return r; }
; __device__ __forceinline__ void store8bf(u16* dst, f32x4 v0, f32x4 v1) { u32x4 w; w.x = pk2(v0[0], v0[1]); w.y = pk2(v0[2], v0[3]); w.z = pk2(v1[0], v1[1]); w.w = pk2(v1[2], v1[3]); *(u32x4*)dst = w; }
.LBB0_761:
	s_add_u32 s24, s36, s20
	v_and_b32_e32 v60, 0xff8, v122
	s_addc_u32 s25, s37, s21
	v_lshl_add_u64 v[58:59], s[24:25], 0, v[68:69]
	v_lshlrev_b32_e32 v140, 1, v60
	v_lshl_add_u64 v[58:59], v[58:59], 0, v[140:141]
	v_cvt_pk_bf16_f32 v54, v54, v55
	v_cvt_pk_bf16_f32 v55, v56, v57
	v_cvt_pk_bf16_f32 v56, v50, v51
	v_cvt_pk_bf16_f32 v57, v52, v53
	global_store_dwordx4 v[58:59], v[54:57], off nt
.LBB0_762:
	s_or_b64 exec, exec, s[22:23]
	v_add_u32_e32 v52, 0x90, v152
	v_mad_i64_i32 v[50:51], s[22:23], v52, s45, 0
	s_and_saveexec_b64 s[22:23], s[2:3]
	s_xor_b64 s[22:23], exec, s[22:23]
	s_cbranch_execz .LBB0_765
	s_cmpk_gt_u32 s13, 0x317f
	s_cbranch_scc1 .LBB0_765
	v_lshl_add_u64 v[54:55], s[8:9], 0, v[50:51]
	v_mov_b32_e32 v151, v141
	v_lshl_add_u64 v[58:59], v[150:151], 1, v[54:55]
	v_add_co_u32_e32 v58, vcc, 0xffffa000, v58
	v_cvt_pk_bf16_f32 v54, v46, v47
	v_cvt_pk_bf16_f32 v55, v48, v49
	v_cvt_pk_bf16_f32 v56, v42, v43
	v_cvt_pk_bf16_f32 v57, v44, v45
	s_nop 1
	v_addc_co_u32_e32 v59, vcc, -1, v59, vcc
	global_store_dwordx4 v[58:59], v[54:57], off nt

; __device__ __forceinline__ unsigned pk2(float lo, float hi) { unsigned r; asm volatile("v_cvt_pk_bf16_f32 %0, %1, %2" : "=v"(r) : "v"(lo), "v"(hi)); return r; }
; __device__ __forceinline__ void store8bf(u16* dst, f32x4 v0, f32x4 v1) { u32x4 w; w.x = pk2(v0[0], v0[1]); w.y = pk2(v0[2], v0[3]); w.z = pk2(v1[0], v1[1]); w.w = pk2(v1[2], v1[3]); *(u32x4*)dst = w; }
.LBB0_768:
	s_add_u32 s24, s36, s20
	v_and_b32_e32 v44, 0xff8, v122
	s_addc_u32 s25, s37, s21
	v_lshl_add_u64 v[42:43], s[24:25], 0, v[52:53]
	v_lshlrev_b32_e32 v140, 1, v44
	v_lshl_add_u64 v[42:43], v[42:43], 0, v[140:141]
	v_cvt_pk_bf16_f32 v38, v38, v39
	v_cvt_pk_bf16_f32 v39, v40, v41
	v_cvt_pk_bf16_f32 v40, v34, v35
	v_cvt_pk_bf16_f32 v41, v36, v37
	global_store_dwordx4 v[42:43], v[38:41], off nt
.LBB0_769:
	s_or_b64 exec, exec, s[22:23]
	v_add_u32_e32 v36, 0xa0, v152
	v_mad_i64_i32 v[34:35], s[22:23], v36, s45, 0
	s_and_saveexec_b64 s[22:23], s[2:3]
	s_xor_b64 s[22:23], exec, s[22:23]
	s_cbranch_execz .LBB0_772
	s_cmpk_gt_u32 s13, 0x317f
	s_cbranch_scc1 .LBB0_772
	v_lshl_add_u64 v[38:39], s[8:9], 0, v[34:35]
	v_mov_b32_e32 v151, v141
	v_lshl_add_u64 v[42:43], v[150:151], 1, v[38:39]
	v_add_co_u32_e32 v42, vcc, 0xffffa000, v42
	v_cvt_pk_bf16_f32 v38, v30, v31
	v_cvt_pk_bf16_f32 v39, v32, v33
	v_cvt_pk_bf16_f32 v40, v26, v27
	v_cvt_pk_bf16_f32 v41, v28, v29
	s_nop 1
	v_addc_co_u32_e32 v43, vcc, -1, v43, vcc
	global_store_dwordx4 v[42:43], v[38:41], off nt

; __device__ __forceinline__ unsigned pk2(float lo, float hi) { unsigned r; asm volatile("v_cvt_pk_bf16_f32 %0, %1, %2" : "=v"(r) : "v"(lo), "v"(hi)); return r; }
; __device__ __forceinline__ void store8bf(u16* dst, f32x4 v0, f32x4 v1) { u32x4 w; w.x = pk2(v0[0], v0[1]); w.y = pk2(v0[2], v0[3]); w.z = pk2(v1[0], v1[1]); w.w = pk2(v1[2], v1[3]); *(u32x4*)dst = w; }
.LBB0_775:
	s_add_u32 s24, s36, s20
	v_and_b32_e32 v28, 0xff8, v122
	s_addc_u32 s25, s37, s21
	v_lshl_add_u64 v[26:27], s[24:25], 0, v[36:37]
	v_lshlrev_b32_e32 v140, 1, v28
	v_lshl_add_u64 v[26:27], v[26:27], 0, v[140:141]
	v_cvt_pk_bf16_f32 v22, v22, v23
	v_cvt_pk_bf16_f32 v23, v24, v25
	v_cvt_pk_bf16_f32 v24, v18, v19
	v_cvt_pk_bf16_f32 v25, v20, v21
	global_store_dwordx4 v[26:27], v[22:25], off nt
.LBB0_776:
	s_or_b64 exec, exec, s[22:23]
	v_add_u32_e32 v20, 0xb0, v152
	v_mad_i64_i32 v[18:19], s[22:23], v20, s45, 0
	s_and_saveexec_b64 s[22:23], s[2:3]
	s_xor_b64 s[2:3], exec, s[22:23]
	s_cbranch_execz .LBB0_779
	s_cmpk_gt_u32 s13, 0x317f
	s_cbranch_scc1 .LBB0_779
	v_lshl_add_u64 v[22:23], s[8:9], 0, v[18:19]
	v_mov_b32_e32 v151, v141
	v_lshl_add_u64 v[26:27], v[150:151], 1, v[22:23]
	v_add_co_u32_e32 v26, vcc, 0xffffa000, v26
	v_cvt_pk_bf16_f32 v22, v14, v15
	v_cvt_pk_bf16_f32 v23, v16, v17
	v_cvt_pk_bf16_f32 v24, v10, v11
	v_cvt_pk_bf16_f32 v25, v12, v13
	s_nop 1
	v_addc_co_u32_e32 v27, vcc, -1, v27, vcc
	global_store_dwordx4 v[26:27], v[22:25], off nt

; __device__ __forceinline__ unsigned pk2(float lo, float hi) { unsigned r; asm volatile("v_cvt_pk_bf16_f32 %0, %1, %2" : "=v"(r) : "v"(lo), "v"(hi)); return r; }
; __device__ __forceinline__ void store8bf(u16* dst, f32x4 v0, f32x4 v1) { u32x4 w; w.x = pk2(v0[0], v0[1]); w.y = pk2(v0[2], v0[3]); w.z = pk2(v1[0], v1[1]); w.w = pk2(v1[2], v1[3]); *(u32x4*)dst = w; }
.LBB0_782:
	s_add_u32 s24, s36, s20
	v_and_b32_e32 v120, 0xf78, v150
	s_addc_u32 s25, s37, s21
	v_lshl_add_u64 v[118:119], s[24:25], 0, v[116:117]
	v_lshlrev_b32_e32 v140, 1, v120
	v_lshl_add_u64 v[118:119], v[118:119], 0, v[140:141]
	v_cvt_pk_bf16_f32 v110, v110, v111
	v_cvt_pk_bf16_f32 v111, v112, v113
	v_cvt_pk_bf16_f32 v112, v106, v107
	v_cvt_pk_bf16_f32 v113, v108, v109
	global_store_dwordx4 v[118:119], v[110:113], off nt
	s_or_b64 exec, exec, s[22:23]
	s_and_saveexec_b64 s[22:23], s[4:5]
	s_xor_b64 s[22:23], exec, s[22:23]
	s_cbranch_execz .LBB0_739
.LBB0_783:
	v_cmp_gt_u32_e32 vcc, s47, v122
	s_and_saveexec_b64 s[24:25], vcc
	s_cbranch_execz .LBB0_785
	v_lshl_add_u64 v[106:107], s[8:9], 0, v[114:115]
	v_mov_b32_e32 v151, v141
	v_lshl_add_u64 v[110:111], v[150:151], 1, v[106:107]
	v_add_co_u32_e32 v110, vcc, 0xffffb000, v110
	v_cvt_pk_bf16_f32 v106, v102, v103
	v_cvt_pk_bf16_f32 v107, v104, v105
	v_cvt_pk_bf16_f32 v108, v98, v99
	v_cvt_pk_bf16_f32 v109, v100, v101
	s_nop 1
	v_addc_co_u32_e32 v111, vcc, -1, v111, vcc
	global_store_dwordx4 v[110:111], v[106:109], off offset:-3840 nt

; __device__ __forceinline__ unsigned pk2(float lo, float hi) { unsigned r; asm volatile("v_cvt_pk_bf16_f32 %0, %1, %2" : "=v"(r) : "v"(lo), "v"(hi)); return r; }
; __device__ __forceinline__ void store8bf(u16* dst, f32x4 v0, f32x4 v1) { u32x4 w; w.x = pk2(v0[0], v0[1]); w.y = pk2(v0[2], v0[3]); w.z = pk2(v1[0], v1[1]); w.w = pk2(v1[2], v1[3]); *(u32x4*)dst = w; }
.LBB0_786:
	s_add_u32 s24, s36, s20
	v_and_b32_e32 v104, 0xf78, v150
	s_addc_u32 s25, s37, s21
	v_lshl_add_u64 v[102:103], s[24:25], 0, v[100:101]
	v_lshlrev_b32_e32 v140, 1, v104
	v_lshl_add_u64 v[102:103], v[102:103], 0, v[140:141]
	v_cvt_pk_bf16_f32 v94, v94, v95
	v_cvt_pk_bf16_f32 v95, v96, v97
	v_cvt_pk_bf16_f32 v96, v90, v91
	v_cvt_pk_bf16_f32 v97, v92, v93
	global_store_dwordx4 v[102:103], v[94:97], off nt
	s_or_b64 exec, exec, s[22:23]
	s_and_saveexec_b64 s[22:23], s[4:5]
	s_xor_b64 s[22:23], exec, s[22:23]
	s_cbranch_execz .LBB0_746
.LBB0_787:
	v_cmp_gt_u32_e32 vcc, s47, v122
	s_and_saveexec_b64 s[24:25], vcc
	s_cbranch_execz .LBB0_789
	v_lshl_add_u64 v[90:91], s[8:9], 0, v[98:99]
	v_mov_b32_e32 v151, v141
	v_lshl_add_u64 v[94:95], v[150:151], 1, v[90:91]
	v_add_co_u32_e32 v94, vcc, 0xffffb000, v94
	v_cvt_pk_bf16_f32 v90, v86, v87
	v_cvt_pk_bf16_f32 v91, v88, v89
	v_cvt_pk_bf16_f32 v92, v82, v83
	v_cvt_pk_bf16_f32 v93, v84, v85
	s_nop 1
	v_addc_co_u32_e32 v95, vcc, -1, v95, vcc
	global_store_dwordx4 v[94:95], v[90:93], off offset:-3840 nt

; __device__ __forceinline__ unsigned pk2(float lo, float hi) { unsigned r; asm volatile("v_cvt_pk_bf16_f32 %0, %1, %2" : "=v"(r) : "v"(lo), "v"(hi)); return r; }
; __device__ __forceinline__ void store8bf(u16* dst, f32x4 v0, f32x4 v1) { u32x4 w; w.x = pk2(v0[0], v0[1]); w.y = pk2(v0[2], v0[3]); w.z = pk2(v1[0], v1[1]); w.w = pk2(v1[2], v1[3]); *(u32x4*)dst = w; }
.LBB0_790:
	s_add_u32 s24, s36, s20
	v_and_b32_e32 v88, 0xf78, v150
	s_addc_u32 s25, s37, s21
	v_lshl_add_u64 v[86:87], s[24:25], 0, v[84:85]
	v_lshlrev_b32_e32 v140, 1, v88
	v_lshl_add_u64 v[86:87], v[86:87], 0, v[140:141]
	v_cvt_pk_bf16_f32 v78, v78, v79
	v_cvt_pk_bf16_f32 v79, v80, v81
	v_cvt_pk_bf16_f32 v80, v74, v75
	v_cvt_pk_bf16_f32 v81, v76, v77
	global_store_dwordx4 v[86:87], v[78:81], off nt
	s_or_b64 exec, exec, s[22:23]
	s_and_saveexec_b64 s[22:23], s[4:5]
	s_xor_b64 s[22:23], exec, s[22:23]
	s_cbranch_execz .LBB0_753
.LBB0_791:
	v_cmp_gt_u32_e32 vcc, s47, v122
	s_and_saveexec_b64 s[24:25], vcc
	s_cbranch_execz .LBB0_793
	v_lshl_add_u64 v[74:75], s[8:9], 0, v[82:83]
	v_mov_b32_e32 v151, v141
	v_lshl_add_u64 v[78:79], v[150:151], 1, v[74:75]
	v_add_co_u32_e32 v78, vcc, 0xffffb000, v78
	v_cvt_pk_bf16_f32 v74, v70, v71
	v_cvt_pk_bf16_f32 v75, v72, v73
	v_cvt_pk_bf16_f32 v76, v66, v67
	v_cvt_pk_bf16_f32 v77, v68, v69
	s_nop 1
	v_addc_co_u32_e32 v79, vcc, -1, v79, vcc
	global_store_dwordx4 v[78:79], v[74:77], off offset:-3840 nt

; __device__ __forceinline__ unsigned pk2(float lo, float hi) { unsigned r; asm volatile("v_cvt_pk_bf16_f32 %0, %1, %2" : "=v"(r) : "v"(lo), "v"(hi)); return r; }
; __device__ __forceinline__ void store8bf(u16* dst, f32x4 v0, f32x4 v1) { u32x4 w; w.x = pk2(v0[0], v0[1]); w.y = pk2(v0[2], v0[3]); w.z = pk2(v1[0], v1[1]); w.w = pk2(v1[2], v1[3]); *(u32x4*)dst = w; }
.LBB0_794:
	s_add_u32 s24, s36, s20
	v_and_b32_e32 v72, 0xf78, v150
	s_addc_u32 s25, s37, s21
	v_lshl_add_u64 v[70:71], s[24:25], 0, v[68:69]
	v_lshlrev_b32_e32 v140, 1, v72
	v_lshl_add_u64 v[70:71], v[70:71], 0, v[140:141]
	v_cvt_pk_bf16_f32 v62, v62, v63
	v_cvt_pk_bf16_f32 v63, v64, v65
	v_cvt_pk_bf16_f32 v64, v58, v59
	v_cvt_pk_bf16_f32 v65, v60, v61
	global_store_dwordx4 v[70:71], v[62:65], off nt
	s_or_b64 exec, exec, s[22:23]
	s_and_saveexec_b64 s[22:23], s[4:5]
	s_xor_b64 s[22:23], exec, s[22:23]
	s_cbranch_execz .LBB0_760
.LBB0_795:
	v_cmp_gt_u32_e32 vcc, s47, v122
	s_and_saveexec_b64 s[24:25], vcc
	s_cbranch_execz .LBB0_797
	v_lshl_add_u64 v[58:59], s[8:9], 0, v[66:67]
	v_mov_b32_e32 v151, v141
	v_lshl_add_u64 v[62:63], v[150:151], 1, v[58:59]
	v_add_co_u32_e32 v62, vcc, 0xffffb000, v62
	v_cvt_pk_bf16_f32 v58, v54, v55
	v_cvt_pk_bf16_f32 v59, v56, v57
	v_cvt_pk_bf16_f32 v60, v50, v51
	v_cvt_pk_bf16_f32 v61, v52, v53
	s_nop 1
	v_addc_co_u32_e32 v63, vcc, -1, v63, vcc
	global_store_dwordx4 v[62:63], v[58:61], off offset:-3840 nt

; __device__ __forceinline__ unsigned pk2(float lo, float hi) { unsigned r; asm volatile("v_cvt_pk_bf16_f32 %0, %1, %2" : "=v"(r) : "v"(lo), "v"(hi)); return r; }
; __device__ __forceinline__ void store8bf(u16* dst, f32x4 v0, f32x4 v1) { u32x4 w; w.x = pk2(v0[0], v0[1]); w.y = pk2(v0[2], v0[3]); w.z = pk2(v1[0], v1[1]); w.w = pk2(v1[2], v1[3]); *(u32x4*)dst = w; }
.LBB0_798:
	s_add_u32 s24, s36, s20
	v_and_b32_e32 v56, 0xf78, v150
	s_addc_u32 s25, s37, s21
	v_lshl_add_u64 v[54:55], s[24:25], 0, v[52:53]
	v_lshlrev_b32_e32 v140, 1, v56
	v_lshl_add_u64 v[54:55], v[54:55], 0, v[140:141]
	v_cvt_pk_bf16_f32 v46, v46, v47
	v_cvt_pk_bf16_f32 v47, v48, v49
	v_cvt_pk_bf16_f32 v48, v42, v43
	v_cvt_pk_bf16_f32 v49, v44, v45
	global_store_dwordx4 v[54:55], v[46:49], off nt
	s_or_b64 exec, exec, s[22:23]
	s_and_saveexec_b64 s[22:23], s[4:5]
	s_xor_b64 s[22:23], exec, s[22:23]
	s_cbranch_execz .LBB0_767
.LBB0_799:
	v_cmp_gt_u32_e32 vcc, s47, v122
	s_and_saveexec_b64 s[24:25], vcc
	s_cbranch_execz .LBB0_801
	v_lshl_add_u64 v[42:43], s[8:9], 0, v[50:51]
	v_mov_b32_e32 v151, v141
	v_lshl_add_u64 v[46:47], v[150:151], 1, v[42:43]
	v_add_co_u32_e32 v46, vcc, 0xffffb000, v46
	v_cvt_pk_bf16_f32 v42, v38, v39
	v_cvt_pk_bf16_f32 v43, v40, v41
	v_cvt_pk_bf16_f32 v44, v34, v35
	v_cvt_pk_bf16_f32 v45, v36, v37
	s_nop 1
	v_addc_co_u32_e32 v47, vcc, -1, v47, vcc
	global_store_dwordx4 v[46:47], v[42:45], off offset:-3840 nt

; __device__ __forceinline__ unsigned pk2(float lo, float hi) { unsigned r; asm volatile("v_cvt_pk_bf16_f32 %0, %1, %2" : "=v"(r) : "v"(lo), "v"(hi)); return r; }
; __device__ __forceinline__ void store8bf(u16* dst, f32x4 v0, f32x4 v1) { u32x4 w; w.x = pk2(v0[0], v0[1]); w.y = pk2(v0[2], v0[3]); w.z = pk2(v1[0], v1[1]); w.w = pk2(v1[2], v1[3]); *(u32x4*)dst = w; }
.LBB0_802:
	s_add_u32 s24, s36, s20
	v_and_b32_e32 v40, 0xf78, v150
	s_addc_u32 s25, s37, s21
	v_lshl_add_u64 v[38:39], s[24:25], 0, v[36:37]
	v_lshlrev_b32_e32 v140, 1, v40
	v_lshl_add_u64 v[38:39], v[38:39], 0, v[140:141]
	v_cvt_pk_bf16_f32 v30, v30, v31
	v_cvt_pk_bf16_f32 v31, v32, v33
	v_cvt_pk_bf16_f32 v32, v26, v27
	v_cvt_pk_bf16_f32 v33, v28, v29
	global_store_dwordx4 v[38:39], v[30:33], off nt
	s_or_b64 exec, exec, s[22:23]
	s_and_saveexec_b64 s[22:23], s[4:5]
	s_xor_b64 s[22:23], exec, s[22:23]
	s_cbranch_execz .LBB0_774
.LBB0_803:
	v_cmp_gt_u32_e32 vcc, s47, v122
	s_and_saveexec_b64 s[24:25], vcc
	s_cbranch_execz .LBB0_805
	v_lshl_add_u64 v[26:27], s[8:9], 0, v[34:35]
	v_mov_b32_e32 v151, v141
	v_lshl_add_u64 v[30:31], v[150:151], 1, v[26:27]
	v_add_co_u32_e32 v30, vcc, 0xffffb000, v30
	v_cvt_pk_bf16_f32 v26, v22, v23
	v_cvt_pk_bf16_f32 v27, v24, v25
	v_cvt_pk_bf16_f32 v28, v18, v19
	v_cvt_pk_bf16_f32 v29, v20, v21
	s_nop 1
	v_addc_co_u32_e32 v31, vcc, -1, v31, vcc
	global_store_dwordx4 v[30:31], v[26:29], off offset:-3840 nt

; __device__ __forceinline__ unsigned pk2(float lo, float hi) { unsigned r; asm volatile("v_cvt_pk_bf16_f32 %0, %1, %2" : "=v"(r) : "v"(lo), "v"(hi)); return r; }
; __device__ __forceinline__ void store8bf(u16* dst, f32x4 v0, f32x4 v1) { u32x4 w; w.x = pk2(v0[0], v0[1]); w.y = pk2(v0[2], v0[3]); w.z = pk2(v1[0], v1[1]); w.w = pk2(v1[2], v1[3]); *(u32x4*)dst = w; }
.LBB0_806:
	s_add_u32 s22, s36, s20
	v_and_b32_e32 v24, 0xf78, v150
	s_addc_u32 s23, s37, s21
	v_lshl_add_u64 v[22:23], s[22:23], 0, v[20:21]
	v_lshlrev_b32_e32 v140, 1, v24
	v_lshl_add_u64 v[22:23], v[22:23], 0, v[140:141]
	v_cvt_pk_bf16_f32 v14, v14, v15
	v_cvt_pk_bf16_f32 v15, v16, v17
	v_cvt_pk_bf16_f32 v16, v10, v11
	v_cvt_pk_bf16_f32 v17, v12, v13
	global_store_dwordx4 v[22:23], v[14:17], off nt
	s_or_b64 exec, exec, s[2:3]
	s_and_saveexec_b64 s[2:3], s[4:5]
	s_xor_b64 s[2:3], exec, s[2:3]
	s_cbranch_execz .LBB0_781
.LBB0_807:
	v_cmp_gt_u32_e32 vcc, s47, v122
	s_and_saveexec_b64 s[4:5], vcc
	s_cbranch_execz .LBB0_809
	v_lshl_add_u64 v[10:11], s[8:9], 0, v[18:19]
	v_mov_b32_e32 v151, v141
	v_lshl_add_u64 v[14:15], v[150:151], 1, v[10:11]
	v_add_co_u32_e32 v14, vcc, 0xffffb000, v14
	v_cvt_pk_bf16_f32 v10, v6, v7
	v_cvt_pk_bf16_f32 v11, v8, v9
	v_cvt_pk_bf16_f32 v12, v2, v3
	v_cvt_pk_bf16_f32 v13, v4, v5
	s_nop 1
	v_addc_co_u32_e32 v15, vcc, -1, v15, vcc
	global_store_dwordx4 v[14:15], v[10:13], off offset:-3840 nt

; __device__ __forceinline__ unsigned pk2(float lo, float hi) { unsigned r; asm volatile("v_cvt_pk_bf16_f32 %0, %1, %2" : "=v"(r) : "v"(lo), "v"(hi)); return r; }
; __device__ __forceinline__ void store8bf(u16* dst, f32x4 v0, f32x4 v1) { u32x4 w; w.x = pk2(v0[0], v0[1]); w.y = pk2(v0[2], v0[3]); w.z = pk2(v1[0], v1[1]); w.w = pk2(v1[2], v1[3]); *(u32x4*)dst = w; }
.LBB0_810:
	s_add_u32 s4, s36, s20
	v_and_b32_e32 v12, 0xff8, v122
	s_addc_u32 s5, s37, s21
	v_lshl_add_u64 v[10:11], s[4:5], 0, v[20:21]
	v_lshlrev_b32_e32 v140, 1, v12
	v_lshl_add_u64 v[10:11], v[10:11], 0, v[140:141]
	v_cvt_pk_bf16_f32 v6, v6, v7
	v_cvt_pk_bf16_f32 v7, v8, v9
	v_cvt_pk_bf16_f32 v8, v2, v3
	v_cvt_pk_bf16_f32 v9, v4, v5
	global_store_dwordx4 v[10:11], v[6:9], off nt
	s_branch .LBB0_718
